# v94 + GU GEMM: next-tile decode (55 SALU + 4 VALU per tile, serial at tile start) issued between the MFMAs of the tile's first MFMA block, branch-free
# speedup vs baseline: 1.0022x; 1.0022x over previous
; #define PG8_STAGE(bufoff, gbase, voff) do { _Pragma("unroll") for (int _i = 0; _i < 2; ++_i) \
;         __builtin_amdgcn_global_load_lds((const unsigned*)((const char*)(gbase) + (voff)[_i]), (PG8_LAS unsigned*)(lds + (bufoff) + ldsw + _i * 8192), 16, 0, 0); } while (0)
; #define PG8_LDA(dst, b, h) do { _Pragma("unroll") for (int m = 0; m < 4; ++m) _Pragma("unroll") for (int k = 0; k < 2; ++k) dst[m][k] = *(const PG8_LAS bf16x8*)(lds + PG8_SA(b, h) + aoff + m * 2048 + k * 1024); } while (0)
; #define PG8_LDB(dst, b, h) do { _Pragma("unroll") for (int n = 0; n < 2; ++n) _Pragma("unroll") for (int k = 0; k < 2; ++k) dst[n][k] = *(const PG8_LAS bf16x8*)(lds + PG8_SB(b, h) + boff + n * 2048 + k * 1024); } while (0)
; #define PG8_BAR __builtin_amdgcn_s_barrier()
;     __host__ __device__ bool next(int i, Unit& u) const {
;         const long L = (long)i * G + c; if (L >= nwg) return false;
;         int wgid = (int)L; { const int q = nwg / NXCD, r = nwg % NXCD, xcd = wgid % NXCD, off = wgid / NXCD; wgid = (xcd < r ? xcd * (q + 1) : r * (q + 1) + (xcd - r) * q) + off; }
;         const int nig = WGM * nN, gid = wgid / nig, fm = gid * WGM, gsz = (nM - fm) < WGM ? (nM - fm) : WGM;
;         u.pm = fm + ((wgid % nig) % gsz); u.pn = (wgid % nig) / gsz; return true;
;     }
; template <class Epi, class Sched, bool ALIGN_EPI = false, bool SP2 = false>
; __device__ __forceinline__ void gemm_phase(PG8_LAS unsigned char* lds, const Gemm g, const Sched& S, const Epi& E) {
;     ...
;         const bool has_next = S.next(ui + 1, nxt);
;         const char* nA = has_next ? (const char*)g.A + (size_t)nxt.pm * tstep : cA; const char* nB = has_next ? (const char*)g.Bt + (size_t)nxt.pn * tstep : cB;
;         for (int t = 0; t < nt; t += 2) {
;             const bool last = (t == nt - 2);
;             const char* a1 = cA + (size_t)(t + 1) * kstep;
;             const char* a2 = last ? nA : cA + (size_t)(t + 2) * kstep; const char* b2 = last ? nB : cB + (size_t)(t + 2) * kstep;
;             const char* a3 = a2 + kstep; const char* b3 = b2 + kstep;
;             if (last && has_next) S.a_ready(nxt);
;             if constexpr (SP2) {
;             PG8_LDB(B0, 0, 0); PG8_LDB(B1, 0, 1); PG8_SCHED; PG8_LDA(At, 0, 0); PG8_STAGE(PG8_SA(1, 1), a1 + hstep, voffA);
;             PG8_WAIT_V(8); PG8_WAIT_L(0); PG8_BAR; PG8_MMA(0, 0, At, B0); PG8_MMA(0, 1, At, B1); PG8_BAR; PG8_SCHED;
.LBB0_402:
	s_add_u32 s8, s8, 0x40080
	s_addc_u32 s9, s9, 0
	s_add_u32 s44, s24, 0x100
	s_addc_u32 s45, s25, 0
	s_mov_b32 s46, -2
	s_add_u32 s24, s8, 0xfffc0080
	s_addc_u32 s25, s9, -1
	s_cmp_eq_u32 s46, 12
	s_cselect_b32 s27, s7, s25
	s_cselect_b32 s26, s17, s24
	s_cselect_b32 s25, s19, s45
	s_cselect_b32 s24, s43, s44
	s_add_i32 s50, 0, 0x14000
	ds_read_b128 v[144:147], v164
	ds_read_b128 v[148:151], v164 offset:1024
	ds_read_b128 v[152:155], v164 offset:2048
	ds_read_b128 v[156:159], v164 offset:3072
	ds_read_b128 v[160:163], v164 offset:16384
	ds_read_b128 v[168:171], v164 offset:17408
	ds_read_b128 v[172:175], v164 offset:18432
	ds_read_b128 v[176:179], v164 offset:19456
	v_lshl_add_u64 v[198:199], s[8:9], 0, v[140:141]
	s_add_i32 m0, s37, 0xc000
	ds_read_b128 v[180:183], v166
	ds_read_b128 v[184:187], v166 offset:1024
	ds_read_b128 v[188:191], v166 offset:2048
	ds_read_b128 v[192:195], v166 offset:3072
	ds_read_b128 v[202:205], v166 offset:4096
	ds_read_b128 v[206:209], v166 offset:5120
	ds_read_b128 v[210:213], v166 offset:6144
	ds_read_b128 v[214:217], v166 offset:7168
	global_load_lds_dwordx4 v[198:199], off
	s_add_i32 m0, s37, 0xe000
	v_lshl_add_u64 v[198:199], s[8:9], 0, v[142:143]
	global_load_lds_dwordx4 v[198:199], off
	s_waitcnt vmcnt(8) lgkmcnt(0)
	s_barrier
	s_setprio 1
	v_mfma_f32_16x16x32_bf16 v[128:131], v[144:147], v[180:183], 0
	v_mfma_f32_16x16x32_bf16 v[120:123], v[152:155], v[180:183], 0
	s_add_i32 s72, s72, 1
	s_lshl_b64 s[4:5], s[72:73], 8
	v_mfma_f32_16x16x32_bf16 v[112:115], v[144:147], v[188:191], 0
	s_add_u32 s20, s4, s28
	s_addc_u32 s21, s5, s36
	v_mfma_f32_16x16x32_bf16 v[104:107], v[152:155], v[188:191], 0
	s_cmp_lt_u32 s20, 0xb00
	s_cselect_b64 s[4:5], -1, 0
	v_mfma_f32_16x16x32_bf16 v[96:99], v[144:147], v[202:205], 0
	s_cmp_eq_u32 s21, 0
	s_cselect_b64 vcc, -1, 0
	v_mfma_f32_16x16x32_bf16 v[88:91], v[152:155], v[202:205], 0
	s_and_b64 s[4:5], s[4:5], vcc
	s_ashr_i32 s7, s20, 31
	v_mfma_f32_16x16x32_bf16 v[80:83], v[144:147], v[210:213], 0
	s_lshr_b32 s7, s7, 29
	s_add_i32 s7, s20, s7
	v_mfma_f32_16x16x32_bf16 v[72:75], v[152:155], v[210:213], 0
	s_ashr_i32 s16, s7, 3
	s_and_b32 s7, s7, -8
	v_mfma_f32_16x16x32_bf16 v[128:131], v[148:151], v[184:187], v[128:131]
	s_sub_i32 s7, s20, s7
	s_cmp_lt_i32 s7, 0
	v_mfma_f32_16x16x32_bf16 v[120:123], v[156:159], v[184:187], v[120:123]
	s_cselect_b32 s17, s74, 0x160
	s_mul_i32 s7, s7, s17
	v_mfma_f32_16x16x32_bf16 v[112:115], v[148:151], v[192:195], v[112:115]
	s_add_i32 s7, s7, s16
	s_mul_hi_i32 s16, s7, 0x2e8ba2e9
	v_mfma_f32_16x16x32_bf16 v[104:107], v[156:159], v[192:195], v[104:107]
	s_lshr_b32 s17, s16, 31
	s_ashr_i32 s16, s16, 5
	v_mfma_f32_16x16x32_bf16 v[96:99], v[148:151], v[206:209], v[96:99]
	s_add_i32 s16, s16, s17
	s_lshl_b32 s17, s16, 3
	v_mfma_f32_16x16x32_bf16 v[88:91], v[156:159], v[206:209], v[88:91]
	s_mulk_i32 s16, 0xb0
	s_sub_i32 s7, s7, s16
	v_mfma_f32_16x16x32_bf16 v[80:83], v[148:151], v[214:217], v[80:83]
	s_bfe_u32 s16, s7, 0x3001c
	s_add_i32 s16, s7, s16
	v_mfma_f32_16x16x32_bf16 v[72:75], v[156:159], v[214:217], v[72:75]
	s_sext_i32_i16 s18, s16
	s_and_b32 s16, s16, 0xfff8
	s_setprio 0
	s_setprio 1
	v_mfma_f32_16x16x32_bf16 v[124:127], v[160:163], v[180:183], 0
	s_sub_i32 s7, s7, s16
	s_sext_i32_i16 s7, s7
	v_mfma_f32_16x16x32_bf16 v[116:119], v[172:175], v[180:183], 0
	s_add_i32 s16, s17, s7
	s_ashr_i32 s18, s18, 3
	v_mfma_f32_16x16x32_bf16 v[108:111], v[160:163], v[188:191], 0
	s_ashr_i32 s17, s16, 31
	s_lshl_b64 s[20:21], s[16:17], 19
	v_mfma_f32_16x16x32_bf16 v[100:103], v[172:175], v[188:191], 0
	s_add_u32 s20, s29, s20
	s_addc_u32 s21, s30, s21
	v_mfma_f32_16x16x32_bf16 v[92:95], v[160:163], v[202:205], 0
	s_add_u32 s22, s8, 0xfffbff80
	s_addc_u32 s23, s9, -1
	v_mfma_f32_16x16x32_bf16 v[84:87], v[172:175], v[202:205], 0
	s_and_b64 vcc, s[4:5], exec
	s_cselect_b32 s7, s21, s23
	v_mfma_f32_16x16x32_bf16 v[76:79], v[160:163], v[210:213], 0
	s_cselect_b32 s17, s20, s22
	s_ashr_i32 s19, s18, 31
	v_mfma_f32_16x16x32_bf16 v[68:71], v[172:175], v[210:213], 0
	s_lshl_b64 s[22:23], s[18:19], 19
	s_add_u32 s22, s31, s22
	v_mfma_f32_16x16x32_bf16 v[124:127], v[168:171], v[184:187], v[124:127]
	s_addc_u32 s23, s34, s23
	s_add_u32 s100, s44, 0xffffff00
	v_mfma_f32_16x16x32_bf16 v[116:119], v[176:179], v[184:187], v[116:119]
	s_addc_u32 s101, s45, -1
	s_and_b64 vcc, s[4:5], exec
	v_mfma_f32_16x16x32_bf16 v[108:111], v[168:171], v[192:195], v[108:111]
	s_cselect_b32 s19, s23, s101
	s_cselect_b32 s43, s22, s100
	v_mfma_f32_16x16x32_bf16 v[100:103], v[176:179], v[192:195], v[100:103]
	v_mfma_f32_16x16x32_bf16 v[92:95], v[168:171], v[206:209], v[92:95]
	v_mfma_f32_16x16x32_bf16 v[84:87], v[176:179], v[206:209], v[84:87]
	v_mfma_f32_16x16x32_bf16 v[76:79], v[168:171], v[214:217], v[76:79]
	v_mfma_f32_16x16x32_bf16 v[68:71], v[176:179], v[214:217], v[68:71]
	s_setprio 0
	s_barrier
; #define PG8_STAGE(bufoff, gbase, voff) do { _Pragma("unroll") for (int _i = 0; _i < 2; ++_i) \
;         __builtin_amdgcn_global_load_lds((const unsigned*)((const char*)(gbase) + (voff)[_i]), (PG8_LAS unsigned*)(lds + (bufoff) + ldsw + _i * 8192), 16, 0, 0); } while (0)
; #define PG8_LDA(dst, b, h) do { _Pragma("unroll") for (int m = 0; m < 4; ++m) _Pragma("unroll") for (int k = 0; k < 2; ++k) dst[m][k] = *(const PG8_LAS bf16x8*)(lds + PG8_SA(b, h) + aoff + m * 2048 + k * 1024); } while (0)
; #define PG8_MMA(ai, bj, At, Bt) do { __builtin_amdgcn_s_setprio(1); _Pragma("unroll") for (int m = 0; m < 4; ++m) _Pragma("unroll") for (int n = 0; n < 2; ++n) _Pragma("unroll") for (int k = 0; k < 2; ++k) \
;         acc[ai][bj][m][n] = __builtin_amdgcn_mfma_f32_16x16x32_bf16(Bt[n][k], At[m][k], acc[ai][bj][m][n], 0, 0, 0); __builtin_amdgcn_s_setprio(0); } while (0)
; #define PG8_WAIT_V(n) asm volatile("s_waitcnt vmcnt(" #n ")" ::: "memory")
; #define PG8_WAIT_L(n) asm volatile("s_waitcnt lgkmcnt(" #n ")" ::: "memory")
; #define PG8_BAR __builtin_amdgcn_s_barrier()
; #define PG8_SCHED __builtin_amdgcn_sched_barrier(0)
; template <class Epi, class Sched, bool ALIGN_EPI = false, bool SP2 = false>
; __device__ __forceinline__ void gemm_phase(PG8_LAS unsigned char* lds, const Gemm g, const Sched& S, const Epi& E) {
;     ...
;             PG8_LDA(At, 0, 1); PG8_STAGE(PG8_SB(0, 0), b2, voffB); PG8_STAGE(PG8_SB(0, 1), b2 + hstep, voffB); PG8_STAGE(PG8_SA(0, 0), a2, voffA);
;             PG8_WAIT_V(8); PG8_WAIT_L(0); PG8_BAR; PG8_MMA(1, 0, At, B0); PG8_MMA(1, 1, At, B1); PG8_BAR; PG8_SCHED;
	v_lshl_add_u64 v[198:199], s[24:25], 0, v[134:135]
	s_add_i32 m0, s35, 0x10000
	ds_read_b128 v[180:183], v166 offset:16384
	ds_read_b128 v[184:187], v166 offset:17408
	ds_read_b128 v[188:191], v166 offset:18432
	ds_read_b128 v[192:195], v166 offset:19456
	ds_read_b128 v[202:205], v166 offset:20480
	ds_read_b128 v[206:209], v166 offset:21504
	ds_read_b128 v[210:213], v166 offset:22528
	ds_read_b128 v[214:217], v166 offset:23552
	global_load_lds_dwordx4 v[198:199], off
	s_add_i32 m0, s35, 0x12000
	s_add_u32 s48, s24, 0x40000
	v_lshl_add_u64 v[218:219], s[24:25], 0, v[0:1]
	s_addc_u32 s49, s25, 0
	global_load_lds_dwordx4 v[218:219], off
	v_lshl_add_u64 v[220:221], s[48:49], 0, v[134:135]
	s_add_i32 m0, s35, 0x14000
	v_lshl_add_u64 v[222:223], s[26:27], 0, v[132:133]
	global_load_lds_dwordx4 v[220:221], off
	s_add_i32 m0, s35, 0x16000
	v_lshl_add_u64 v[220:221], s[48:49], 0, v[0:1]
	global_load_lds_dwordx4 v[220:221], off
	s_mov_b32 m0, s37
	v_lshl_add_u64 v[220:221], s[26:27], 0, v[136:137]
	global_load_lds_dwordx4 v[220:221], off
	s_mov_b32 m0, s38
	s_add_i32 s47, 0, 0x18000
	global_load_lds_dwordx4 v[222:223], off
	s_waitcnt vmcnt(8) lgkmcnt(0)
	s_barrier
	s_setprio 1
	v_mfma_f32_16x16x32_bf16 v[64:67], v[144:147], v[180:183], 0
	v_mfma_f32_16x16x32_bf16 v[56:59], v[152:155], v[180:183], 0
	v_mfma_f32_16x16x32_bf16 v[48:51], v[144:147], v[188:191], 0
	v_mfma_f32_16x16x32_bf16 v[40:43], v[152:155], v[188:191], 0
	v_mfma_f32_16x16x32_bf16 v[32:35], v[144:147], v[202:205], 0
	v_mfma_f32_16x16x32_bf16 v[24:27], v[152:155], v[202:205], 0
	v_mfma_f32_16x16x32_bf16 v[16:19], v[144:147], v[210:213], 0
	v_mfma_f32_16x16x32_bf16 v[8:11], v[152:155], v[210:213], 0
	v_mfma_f32_16x16x32_bf16 v[64:67], v[148:151], v[184:187], v[64:67]
	v_mfma_f32_16x16x32_bf16 v[56:59], v[156:159], v[184:187], v[56:59]
	v_mfma_f32_16x16x32_bf16 v[48:51], v[148:151], v[192:195], v[48:51]
	v_mfma_f32_16x16x32_bf16 v[40:43], v[156:159], v[192:195], v[40:43]
	v_mfma_f32_16x16x32_bf16 v[32:35], v[148:151], v[206:209], v[32:35]
	v_mfma_f32_16x16x32_bf16 v[24:27], v[156:159], v[206:209], v[24:27]
	v_mfma_f32_16x16x32_bf16 v[16:19], v[148:151], v[214:217], v[16:19]
	v_mfma_f32_16x16x32_bf16 v[8:11], v[156:159], v[214:217], v[8:11]
	s_setprio 0
	s_setprio 1
	v_mfma_f32_16x16x32_bf16 v[60:63], v[160:163], v[180:183], 0
	v_mfma_f32_16x16x32_bf16 v[52:55], v[172:175], v[180:183], 0
	v_mfma_f32_16x16x32_bf16 v[44:47], v[160:163], v[188:191], 0
	v_mfma_f32_16x16x32_bf16 v[36:39], v[172:175], v[188:191], 0
	v_mfma_f32_16x16x32_bf16 v[28:31], v[160:163], v[202:205], 0
	v_mfma_f32_16x16x32_bf16 v[20:23], v[172:175], v[202:205], 0
	v_mfma_f32_16x16x32_bf16 v[12:15], v[160:163], v[210:213], 0
	v_mfma_f32_16x16x32_bf16 v[4:7], v[172:175], v[210:213], 0
	v_mfma_f32_16x16x32_bf16 v[60:63], v[168:171], v[184:187], v[60:63]
	v_mfma_f32_16x16x32_bf16 v[52:55], v[176:179], v[184:187], v[52:55]
	v_mfma_f32_16x16x32_bf16 v[44:47], v[168:171], v[192:195], v[44:47]
	v_mfma_f32_16x16x32_bf16 v[36:39], v[176:179], v[192:195], v[36:39]
	v_mfma_f32_16x16x32_bf16 v[28:31], v[168:171], v[206:209], v[28:31]
	v_mfma_f32_16x16x32_bf16 v[20:23], v[176:179], v[206:209], v[20:23]
	v_mfma_f32_16x16x32_bf16 v[12:15], v[168:171], v[214:217], v[12:15]
	v_mfma_f32_16x16x32_bf16 v[4:7], v[176:179], v[214:217], v[4:7]
	s_setprio 0
	s_barrier
	s_branch .Lkmid_2
